# prologue de-serialisation in all 8 GEMM phases: the three second-batch tile stages are issued with the first batch (first counted wait vmcnt 2 -> 8) instead of after its wait and barrier
# baseline (speedup 1.0000x reference)
; #define PG8_STAGE(bufoff, gbase, voff) do { _Pragma("unroll") for (int _i = 0; _i < 2; ++_i) \
;         __builtin_amdgcn_global_load_lds((const unsigned*)((const char*)(gbase) + (voff)[_i]), (LAS unsigned*)(lds + (bufoff) + ldsw + _i * 8192), 16, 0, 0); } while (0)
; #define PG8_WAIT_V(n) asm volatile("s_waitcnt vmcnt(" #n ")" ::: "memory")
; #define PG8_BAR __builtin_amdgcn_s_barrier()
; template <class Epi, bool ALIGN_EPI>
; __device__ __forceinline__ void gemm_phase(LAS unsigned char* lds, const Gemm g, const StaticOrder& S, const Epi& E) {
;     ...
;     PG8_STAGE(PG8_SB(0, 0), cB, voffB); PG8_STAGE(PG8_SB(0, 1), cB + hstep, voffB); PG8_STAGE(PG8_SA(0, 0), cA, voffA); PG8_STAGE(PG8_SA(0, 1), cA + hstep, voffA);
;     if (wr == 1) PG8_BAR;
;     PG8_WAIT_V(2); PG8_BAR;
;     PG8_STAGE(PG8_SB(1, 0), cB + kstep, voffB); PG8_STAGE(PG8_SA(1, 0), cA + kstep, voffA); PG8_STAGE(PG8_SB(1, 1), cB + hstep + kstep, voffB);
;     PG8_WAIT_V(6); PG8_BAR;
.LBB0_287:
	s_add_u32 s5, s28, 0x9a40000
	s_addc_u32 s90, s29, 0
	s_lshl_b32 s1, s1, 5
	s_mov_b64 s[62:63], 0x80
	s_and_b32 s1, s1, 0x60
	s_add_i32 m0, s76, 0x18000
	v_lshl_add_u64 v[8:9], v[8:9], 0, s[62:63]
	v_writelane_b32 v247, s5, 3
	s_ashr_i32 s91, s3, 31
	s_ashr_i32 s92, s2, 31
	s_lshl_b32 s5, s0, 13
	s_lshl_b32 s9, s1, 7
	global_load_lds_dwordx4 v[8:9], off
	v_lshl_add_u64 v[6:7], v[6:7], 0, s[62:63]
	s_add_i32 m0, s76, 0x1a000
	s_add_i32 s93, s76, 0x8000
	s_add_i32 s94, s76, 0xa000
	global_load_lds_dwordx4 v[6:7], off
	v_lshl_add_u64 v[2:3], v[2:3], 0, s[62:63]
	s_mov_b32 m0, s93
	s_add_u32 s64, s82, 0x40080
	global_load_lds_dwordx4 v[2:3], off
	v_lshl_add_u64 v[2:3], v[4:5], 0, s[62:63]
	s_mov_b32 m0, s94
	s_addc_u32 s65, s83, 0
	global_load_lds_dwordx4 v[2:3], off
	s_add_i32 m0, s76, 0x1c000
	v_lshl_add_u64 v[2:3], s[64:65], 0, v[132:133]
	global_load_lds_dwordx4 v[2:3], off
	v_lshl_add_u64 v[2:3], s[64:65], 0, v[136:137]
	s_add_i32 m0, s76, 0x1e000
	v_lshlrev_b32_e32 v4, 6, v1
	global_load_lds_dwordx4 v[2:3], off
	s_waitcnt vmcnt(8)
	s_barrier
	v_and_b32_e32 v2, 15, v1
	v_lshlrev_b32_e32 v3, 1, v13
	s_movk_i32 s50, 0x3c0
	v_and_or_b32 v4, v4, s50, v3
	v_and_b32_e32 v5, 32, v186
	v_lshl_or_b32 v188, s0, 6, v2
	v_lshl_or_b32 v2, v2, 6, v3
	v_lshlrev_b32_e32 v3, 8, v1
	v_bitop3_b32 v189, s9, v4, v5 bitop3:0xf6
	v_and_b32_e32 v3, 0x38000, v3
	v_lshlrev_b32_e32 v4, 11, v12
	v_or3_b32 v3, v10, v3, v4
	v_add_u32_e32 v140, v3, v11
	v_lshlrev_b32_e32 v3, 4, v14
	s_waitcnt vmcnt(6)
	s_cmpk_lt_u32 s8, 0x100
	v_and_b32_e32 v3, 0x78000, v3
	v_bitop3_b32 v2, v2, s5, v5 bitop3:0xde
	s_cselect_b64 s[64:65], -1, 0
	v_or_b32_e32 v190, s1, v13
	v_or3_b32 v3, v10, v3, v4
	s_add_i32 s95, 0, 0x10000
	s_add_i32 s96, 0, 0x14000
	v_or_b32_e32 v191, 0xfffff800, v190
	v_mov_b32_e32 v141, v139
	v_add_u32_e32 v142, v3, v11
	v_mov_b32_e32 v143, v139
	v_mov_b64_e32 v[144:145], 0x500
	v_mov_b64_e32 v[146:147], 0x4ff
	v_add_u32_e32 v192, s95, v189
	v_add_u32_e32 v193, s96, v189
	v_add_u32_e32 v194, 0, v2
	v_mov_b32_e32 v195, 0x358637bd
	s_mov_b32 s97, 0x800000
	s_barrier
	s_mov_b32 s98, 0
	s_branch .LBB0_290

; #define PG8_STAGE(bufoff, gbase, voff) do { _Pragma("unroll") for (int _i = 0; _i < 2; ++_i) \
;         __builtin_amdgcn_global_load_lds((const unsigned*)((const char*)(gbase) + (voff)[_i]), (LAS unsigned*)(lds + (bufoff) + ldsw + _i * 8192), 16, 0, 0); } while (0)
; #define PG8_WAIT_V(n) asm volatile("s_waitcnt vmcnt(" #n ")" ::: "memory")
; #define PG8_BAR __builtin_amdgcn_s_barrier()
; template <class Epi, bool ALIGN_EPI>
; __device__ __forceinline__ void gemm_phase(LAS unsigned char* lds, const Gemm g, const StaticOrder& S, const Epi& E) {
;     ...
;     PG8_STAGE(PG8_SB(0, 0), cB, voffB); PG8_STAGE(PG8_SB(0, 1), cB + hstep, voffB); PG8_STAGE(PG8_SA(0, 0), cA, voffA); PG8_STAGE(PG8_SA(0, 1), cA + hstep, voffA);
;     if (wr == 1) PG8_BAR;
;     PG8_WAIT_V(2); PG8_BAR;
;     PG8_STAGE(PG8_SB(1, 0), cB + kstep, voffB); PG8_STAGE(PG8_SA(1, 0), cA + kstep, voffA); PG8_STAGE(PG8_SB(1, 1), cB + hstep + kstep, voffB);
;     PG8_WAIT_V(6); PG8_BAR;
.LBB0_510:
	s_lshl_b32 s0, s0, 5
	s_mov_b64 s[18:19], 0x80
	s_and_b32 s52, s0, 0x60
	s_add_i32 m0, s63, 0x18000
	v_lshl_add_u64 v[8:9], v[8:9], 0, s[18:19]
	s_ashr_i32 s76, s3, 31
	s_ashr_i32 s77, s2, 31
	s_lshl_b32 s50, s5, 13
	s_lshl_b32 s51, s52, 7
	global_load_lds_dwordx4 v[8:9], off
	v_lshl_add_u64 v[6:7], v[6:7], 0, s[18:19]
	s_add_i32 m0, s63, 0x1a000
	s_add_i32 s78, s63, 0x8000
	s_add_i32 s79, s63, 0xa000
	global_load_lds_dwordx4 v[6:7], off
	v_lshl_add_u64 v[2:3], v[2:3], 0, s[18:19]
	s_mov_b32 m0, s78
	s_add_u32 s0, s66, 0x40080
	global_load_lds_dwordx4 v[2:3], off
	v_lshl_add_u64 v[2:3], v[4:5], 0, s[18:19]
	s_mov_b32 m0, s79
	s_addc_u32 s1, s67, 0
	global_load_lds_dwordx4 v[2:3], off
	s_add_i32 m0, s63, 0x1c000
	v_lshl_add_u64 v[2:3], s[0:1], 0, v[180:181]
	global_load_lds_dwordx4 v[2:3], off
	v_lshl_add_u64 v[2:3], s[0:1], 0, v[184:185]
	s_add_i32 m0, s63, 0x1e000
	v_lshlrev_b32_e32 v4, 6, v206
	global_load_lds_dwordx4 v[2:3], off
	s_waitcnt vmcnt(8)
	s_barrier
	v_and_b32_e32 v2, 3, v1
	v_lshlrev_b32_e32 v3, 4, v2
	s_movk_i32 s0, 0x3c0
	v_and_or_b32 v4, v4, s0, v3
	v_and_b32_e32 v5, 32, v209
	v_cmp_eq_u32_e64 s[0:1], 0, v2
	v_lshl_or_b32 v213, v2, 3, s52
	v_lshlrev_b32_e32 v2, 8, v206
	v_bitop3_b32 v212, s51, v4, v5 bitop3:0xf6
	v_and_b32_e32 v2, 0x38000, v2
	v_lshlrev_b32_e32 v4, 11, v12
	v_or3_b32 v2, v10, v2, v4
	v_add_u32_e32 v186, v2, v11
	v_lshlrev_b32_e32 v2, 4, v13
	v_lshlrev_b32_e32 v6, 2, v208
	v_and_b32_e32 v2, 0x78000, v2
	v_lshl_or_b32 v3, v208, 6, v3
	v_and_b32_e32 v6, 32, v6
	s_waitcnt vmcnt(6)
	s_cmpk_lt_u32 s4, 0x100
	v_or3_b32 v2, v10, v2, v4
	v_bitop3_b32 v3, v3, s50, v6 bitop3:0xde
	s_cselect_b64 s[50:51], -1, 0
	v_add_u32_e32 v188, v2, v11
	s_add_i32 s80, 0, 0x10000
	s_add_i32 s81, 0, 0x14000
	v_mbcnt_lo_u32_b32 v2, -1, 0
	v_lshl_or_b32 v211, s5, 6, v208
	v_mov_b32_e32 v187, v181
	v_mov_b32_e32 v189, v181
	v_mov_b64_e32 v[190:191], 0x200
	v_mov_b64_e32 v[192:193], 0x1ff
	v_add_u32_e32 v214, s80, v212
	v_add_u32_e32 v215, s81, v212
	v_add_u32_e32 v216, 0, v3
	v_mbcnt_hi_u32_b32 v217, -1, v2
	s_barrier
	s_mov_b32 s98, 0
	s_branch .LBB0_513

; #define PG8_STAGE(bufoff, gbase, voff) do { _Pragma("unroll") for (int _i = 0; _i < 2; ++_i) \
;         __builtin_amdgcn_global_load_lds((const unsigned*)((const char*)(gbase) + (voff)[_i]), (LAS unsigned*)(lds + (bufoff) + ldsw + _i * 8192), 16, 0, 0); } while (0)
; #define PG8_WAIT_V(n) asm volatile("s_waitcnt vmcnt(" #n ")" ::: "memory")
; #define PG8_BAR __builtin_amdgcn_s_barrier()
; template <class Epi, bool ALIGN_EPI>
; __device__ __forceinline__ void gemm_phase(LAS unsigned char* lds, const Gemm g, const StaticOrder& S, const Epi& E) {
;     ...
;     PG8_STAGE(PG8_SB(0, 0), cB, voffB); PG8_STAGE(PG8_SB(0, 1), cB + hstep, voffB); PG8_STAGE(PG8_SA(0, 0), cA, voffA); PG8_STAGE(PG8_SA(0, 1), cA + hstep, voffA);
;     if (wr == 1) PG8_BAR;
;     PG8_WAIT_V(2); PG8_BAR;
;     PG8_STAGE(PG8_SB(1, 0), cB + kstep, voffB); PG8_STAGE(PG8_SA(1, 0), cA + kstep, voffA); PG8_STAGE(PG8_SB(1, 1), cB + hstep + kstep, voffB);
;     PG8_WAIT_V(6); PG8_BAR;
.LBB0_603:
	s_lshl_b32 s5, s11, 5
	s_mov_b64 s[56:57], 0x80
	s_and_b32 s11, s5, 0x60
	s_add_i32 m0, s70, 0x18000
	v_lshl_add_u64 v[8:9], v[8:9], 0, s[56:57]
	s_ashr_i32 s77, s3, 31
	s_lshl_b32 s14, s10, 13
	s_lshl_b32 s15, s11, 7
	global_load_lds_dwordx4 v[8:9], off
	v_lshl_add_u64 v[6:7], v[6:7], 0, s[56:57]
	s_add_i32 m0, s70, 0x1a000
	s_add_i32 s78, s70, 0x8000
	s_add_i32 s79, s70, 0xa000
	global_load_lds_dwordx4 v[6:7], off
	v_lshl_add_u64 v[2:3], v[2:3], 0, s[56:57]
	s_mov_b32 m0, s78
	s_add_u32 s12, s8, 0x40080
	global_load_lds_dwordx4 v[2:3], off
	v_lshl_add_u64 v[2:3], v[4:5], 0, s[56:57]
	s_mov_b32 m0, s79
	s_addc_u32 s13, s9, 0
	global_load_lds_dwordx4 v[2:3], off
	s_add_i32 m0, s70, 0x1c000
	v_lshl_add_u64 v[2:3], s[12:13], 0, v[132:133]
	global_load_lds_dwordx4 v[2:3], off
	v_lshl_add_u64 v[2:3], s[12:13], 0, v[136:137]
	s_add_i32 m0, s70, 0x1e000
	s_sext_i32_i16 s5, s0
	global_load_lds_dwordx4 v[2:3], off
	s_waitcnt vmcnt(8)
	s_barrier
	v_and_b32_e32 v2, 15, v162
	v_lshlrev_b32_e32 v3, 1, v13
	v_lshlrev_b32_e32 v4, 6, v162
	s_movk_i32 s0, 0x3c0
	v_and_or_b32 v4, v4, s0, v3
	v_and_b32_e32 v5, 32, v163
	v_lshl_or_b32 v165, s10, 6, v2
	v_lshl_or_b32 v2, v2, 6, v3
	v_lshlrev_b32_e32 v3, 8, v162
	v_bitop3_b32 v166, s15, v4, v5 bitop3:0xf6
	v_and_b32_e32 v3, 0x38000, v3
	v_lshlrev_b32_e32 v4, 11, v12
	v_or3_b32 v3, v10, v3, v4
	v_add_u32_e32 v138, v3, v11
	v_lshlrev_b32_e32 v3, 4, v14
	s_waitcnt vmcnt(6)
	s_cmpk_lt_u32 s1, 0x100
	v_and_b32_e32 v3, 0x78000, v3
	v_bitop3_b32 v2, v2, s14, v5 bitop3:0xde
	s_cselect_b64 s[58:59], -1, 0
	v_or3_b32 v3, v10, v3, v4
	s_add_i32 s80, 0, 0x10000
	s_add_i32 s81, 0, 0x14000
	v_or_b32_e32 v167, s11, v13
	v_mov_b32_e32 v139, v133
	v_add_u32_e32 v140, v3, v11
	v_mov_b32_e32 v141, v133
	v_mov_b64_e32 v[142:143], 0xb00
	v_mov_b64_e32 v[144:145], 0xaff
	v_add_u32_e32 v168, s80, v166
	v_add_u32_e32 v169, s81, v166
	v_add_u32_e32 v170, 0, v2
	v_mov_b32_e32 v171, 0x358637bd
	s_mov_b32 s82, 0x800000
	s_movk_i32 s83, 0x1600
	s_barrier
	s_mov_b32 s98, 0
	s_branch .LBB0_606

; #define PG8_STAGE(bufoff, gbase, voff) do { _Pragma("unroll") for (int _i = 0; _i < 2; ++_i) \
;         __builtin_amdgcn_global_load_lds((const unsigned*)((const char*)(gbase) + (voff)[_i]), (LAS unsigned*)(lds + (bufoff) + ldsw + _i * 8192), 16, 0, 0); } while (0)
; #define PG8_WAIT_V(n) asm volatile("s_waitcnt vmcnt(" #n ")" ::: "memory")
; #define PG8_BAR __builtin_amdgcn_s_barrier()
; template <class Epi, bool ALIGN_EPI>
; __device__ __forceinline__ void gemm_phase(LAS unsigned char* lds, const Gemm g, const StaticOrder& S, const Epi& E) {
;     ...
;     PG8_STAGE(PG8_SB(0, 0), cB, voffB); PG8_STAGE(PG8_SB(0, 1), cB + hstep, voffB); PG8_STAGE(PG8_SA(0, 0), cA, voffA); PG8_STAGE(PG8_SA(0, 1), cA + hstep, voffA);
;     if (wr == 1) PG8_BAR;
;     PG8_WAIT_V(2); PG8_BAR;
;     PG8_STAGE(PG8_SB(1, 0), cB + kstep, voffB); PG8_STAGE(PG8_SA(1, 0), cA + kstep, voffA); PG8_STAGE(PG8_SB(1, 1), cB + hstep + kstep, voffB);
;     PG8_WAIT_V(6); PG8_BAR;
.LBB0_682:
	s_lshl_b32 s1, s1, 5
	s_mov_b64 s[14:15], 0x80
	s_and_b32 s18, s1, 0x60
	s_add_i32 m0, s58, 0x18000
	v_lshl_add_u64 v[8:9], v[8:9], 0, s[14:15]
	s_lshl_b32 s7, s0, 13
	s_lshl_b32 s1, s18, 7
	global_load_lds_dwordx4 v[8:9], off
	v_lshl_add_u64 v[6:7], v[6:7], 0, s[14:15]
	s_add_i32 m0, s58, 0x1a000
	s_add_i32 s63, s58, 0x8000
	s_add_i32 s64, s58, 0xa000
	global_load_lds_dwordx4 v[6:7], off
	v_lshl_add_u64 v[2:3], v[2:3], 0, s[14:15]
	s_mov_b32 m0, s63
	s_add_u32 s4, s52, 0xb0080
	global_load_lds_dwordx4 v[2:3], off
	v_lshl_add_u64 v[2:3], v[4:5], 0, s[14:15]
	s_mov_b32 m0, s64
	s_addc_u32 s5, s53, 0
	global_load_lds_dwordx4 v[2:3], off
	s_add_i32 m0, s58, 0x1c000
	v_lshl_add_u64 v[2:3], s[4:5], 0, v[156:157]
	global_load_lds_dwordx4 v[2:3], off
	v_lshl_add_u64 v[2:3], s[4:5], 0, v[160:161]
	s_add_i32 m0, s58, 0x1e000
	v_lshlrev_b32_e32 v5, 2, v190
	global_load_lds_dwordx4 v[2:3], off
	s_waitcnt vmcnt(8)
	s_barrier
	v_and_b32_e32 v2, 3, v188
	v_lshlrev_b32_e32 v3, 4, v2
	v_lshl_or_b32 v4, v190, 6, v3
	v_and_b32_e32 v5, 32, v5
	v_lshl_or_b32 v193, s0, 6, v190
	v_bitop3_b32 v4, v4, s7, v5 bitop3:0xde
	v_lshlrev_b32_e32 v5, 6, v189
	s_movk_i32 s0, 0x3c0
	v_and_or_b32 v3, v5, s0, v3
	v_and_b32_e32 v5, 32, v192
	v_bitop3_b32 v194, s1, v3, v5 bitop3:0xf6
	v_cmp_eq_u32_e64 s[0:1], 0, v2
	v_lshl_or_b32 v195, v2, 3, s18
	v_add_u16_e32 v2, v10, v11
	s_waitcnt vmcnt(6)
	s_cmpk_lt_u32 s6, 0x100
	v_lshrrev_b16_e32 v2, 1, v2
	s_cselect_b64 s[16:17], -1, 0
	v_add_lshl_u32 v162, v12, v2, 1
	v_add_lshl_u32 v164, v13, v2, 1
	s_add_i32 s67, 0, 0x10000
	s_add_i32 s68, 0, 0x14000
	v_mbcnt_lo_u32_b32 v2, -1, 0
	s_ashr_i32 s65, s3, 31
	s_ashr_i32 s66, s2, 31
	v_mov_b32_e32 v163, v157
	v_mov_b32_e32 v165, v157
	v_mov_b64_e32 v[166:167], 0x200
	v_mov_b64_e32 v[168:169], 0x1ff
	v_add_u32_e32 v196, s67, v194
	v_add_u32_e32 v197, s68, v194
	v_add_u32_e32 v198, 0, v4
	v_mbcnt_hi_u32_b32 v199, -1, v2
	s_barrier
	s_mov_b32 s98, 0
	s_branch .LBB0_685

; #define PG8_STAGE(bufoff, gbase, voff) do { _Pragma("unroll") for (int _i = 0; _i < 2; ++_i) \
;         __builtin_amdgcn_global_load_lds((const unsigned*)((const char*)(gbase) + (voff)[_i]), (LAS unsigned*)(lds + (bufoff) + ldsw + _i * 8192), 16, 0, 0); } while (0)
; #define PG8_WAIT_V(n) asm volatile("s_waitcnt vmcnt(" #n ")" ::: "memory")
; #define PG8_BAR __builtin_amdgcn_s_barrier()
; template <class Epi, bool ALIGN_EPI>
; __device__ __forceinline__ void gemm_phase(LAS unsigned char* lds, const Gemm g, const StaticOrder& S, const Epi& E) {
;     ...
;     PG8_STAGE(PG8_SB(0, 0), cB, voffB); PG8_STAGE(PG8_SB(0, 1), cB + hstep, voffB); PG8_STAGE(PG8_SA(0, 0), cA, voffA); PG8_STAGE(PG8_SA(0, 1), cA + hstep, voffA);
;     if (wr == 1) PG8_BAR;
;     PG8_WAIT_V(2); PG8_BAR;
;     PG8_STAGE(PG8_SB(1, 0), cB + kstep, voffB); PG8_STAGE(PG8_SA(1, 0), cA + kstep, voffA); PG8_STAGE(PG8_SB(1, 1), cB + hstep + kstep, voffB);
;     PG8_WAIT_V(6); PG8_BAR;
.LBB0_781:
	s_ashr_i32 s15, s3, 31
	s_ashr_i32 s12, s2, 31
	s_add_u32 s13, s74, 0x8900000
	s_addc_u32 s52, s75, 0
	s_add_u32 s56, s74, 0x91c0000
	s_addc_u32 s57, s75, 0
	s_add_u32 s53, s74, 0x8100000
	s_addc_u32 s64, s75, 0
	s_add_u32 s58, s74, 0x9180000
	s_mov_b64 s[60:61], 0x80
	s_addc_u32 s59, s75, 0
	s_and_b32 s10, s0, 3
	s_add_i32 m0, s77, 0x18000
	v_lshl_add_u64 v[8:9], v[8:9], 0, s[60:61]
	s_lshl_b32 s11, s9, 13
	s_lshl_b32 s50, s10, 12
	global_load_lds_dwordx4 v[8:9], off
	v_lshl_add_u64 v[4:5], v[4:5], 0, s[60:61]
	s_add_i32 m0, s77, 0x1a000
	s_add_i32 s65, s77, 0x8000
	s_add_i32 s66, s77, 0xa000
	global_load_lds_dwordx4 v[4:5], off
	v_lshl_add_u64 v[2:3], v[2:3], 0, s[60:61]
	s_mov_b32 m0, s65
	s_add_u32 s0, s6, 0x40080
	global_load_lds_dwordx4 v[2:3], off
	v_lshl_add_u64 v[2:3], v[6:7], 0, s[60:61]
	s_mov_b32 m0, s66
	s_addc_u32 s1, s7, 0
	global_load_lds_dwordx4 v[2:3], off
	s_add_i32 m0, s77, 0x1c000
	v_lshl_add_u64 v[2:3], s[0:1], 0, v[148:149]
	global_load_lds_dwordx4 v[2:3], off
	v_lshl_add_u64 v[2:3], s[0:1], 0, v[152:153]
	s_add_i32 m0, s77, 0x1e000
	v_lshlrev_b32_e32 v4, 6, v210
	global_load_lds_dwordx4 v[2:3], off
	s_waitcnt vmcnt(8)
	s_barrier
	v_and_b32_e32 v2, 3, v157
	v_lshlrev_b32_e32 v3, 4, v2
	s_movk_i32 s0, 0x3c0
	v_lshlrev_b32_e32 v156, 3, v2
	v_and_or_b32 v4, v4, s0, v3
	v_cmp_eq_u32_e64 s[0:1], 0, v2
	v_lshl_or_b32 v2, v211, 6, v3
	v_lshlrev_b32_e32 v3, 2, v211
	v_and_b32_e32 v3, 32, v3
	v_and_b32_e32 v5, 32, v214
	v_bitop3_b32 v2, v2, s11, v3 bitop3:0xde
	v_lshlrev_b32_e32 v3, 8, v210
	v_bitop3_b32 v217, s50, v4, v5 bitop3:0xf6
	v_and_b32_e32 v3, 0x38000, v3
	v_lshlrev_b32_e32 v4, 11, v12
	v_or3_b32 v3, v10, v3, v4
	v_add_u32_e32 v158, v3, v11
	v_lshlrev_b32_e32 v3, 4, v13
	s_waitcnt vmcnt(6)
	s_cmpk_lt_u32 s8, 0x100
	v_and_b32_e32 v3, 0x78000, v3
	v_lshl_or_b32 v216, s9, 6, v211
	s_cselect_b64 s[62:63], -1, 0
	v_or3_b32 v3, v10, v3, v4
	s_add_i32 s69, 0, 0x10000
	s_add_i32 s70, 0, 0x14000
	v_add_u32_e32 v222, 0, v2
	v_mbcnt_lo_u32_b32 v2, -1, 0
	v_add_u32_e32 v218, 0xfffff200, v216
	s_lshl_b32 s67, s10, 3
	s_lshl_b32 s68, s10, 6
	v_lshl_or_b32 v219, s10, 5, v156
	v_mov_b32_e32 v159, v155
	v_add_u32_e32 v160, v3, v11
	v_mov_b32_e32 v161, v155
	v_mov_b64_e32 v[162:163], 0x500
	v_mov_b64_e32 v[164:165], 0x4ff
	v_add_u32_e32 v220, s69, v217
	v_add_u32_e32 v221, s70, v217
	v_mov_b32_e32 v223, 0x358637bd
	s_mov_b32 s71, 0x800000
	s_mov_b64 s[96:97], 0x58000
	v_mbcnt_hi_u32_b32 v224, -1, v2
	v_mov_b32_e32 v225, 0x3e38aa3b
	s_mov_b32 s54, 0
	s_barrier
	s_mov_b32 s98, 0
	s_branch .LBB0_784

; #define PG8_STAGE(bufoff, gbase, voff) do { _Pragma("unroll") for (int _i = 0; _i < 2; ++_i) \
;         __builtin_amdgcn_global_load_lds((const unsigned*)((const char*)(gbase) + (voff)[_i]), (LAS unsigned*)(lds + (bufoff) + ldsw + _i * 8192), 16, 0, 0); } while (0)
; #define PG8_WAIT_V(n) asm volatile("s_waitcnt vmcnt(" #n ")" ::: "memory")
; #define PG8_BAR __builtin_amdgcn_s_barrier()
; template <class Epi, bool ALIGN_EPI>
; __device__ __forceinline__ void gemm_phase(LAS unsigned char* lds, const Gemm g, const StaticOrder& S, const Epi& E) {
;     ...
;     PG8_STAGE(PG8_SB(0, 0), cB, voffB); PG8_STAGE(PG8_SB(0, 1), cB + hstep, voffB); PG8_STAGE(PG8_SA(0, 0), cA, voffA); PG8_STAGE(PG8_SA(0, 1), cA + hstep, voffA);
;     if (wr == 1) PG8_BAR;
;     PG8_WAIT_V(2); PG8_BAR;
;     PG8_STAGE(PG8_SB(1, 0), cB + kstep, voffB); PG8_STAGE(PG8_SA(1, 0), cA + kstep, voffA); PG8_STAGE(PG8_SB(1, 1), cB + hstep + kstep, voffB);
;     PG8_WAIT_V(6); PG8_BAR;
.LBB0_1329:
	s_lshl_b32 s1, s1, 5
	s_mov_b64 s[12:13], 0x80
	s_and_b32 s16, s1, 0x60
	s_add_i32 m0, s39, 0x18000
	v_lshl_add_u64 v[8:9], v[8:9], 0, s[12:13]
	s_lshl_b32 s15, s0, 13
	s_lshl_b32 s1, s16, 7
	global_load_lds_dwordx4 v[8:9], off
	v_lshl_add_u64 v[6:7], v[6:7], 0, s[12:13]
	s_add_i32 m0, s39, 0x1a000
	s_add_i32 s52, s39, 0x8000
	s_add_i32 s53, s39, 0xa000
	global_load_lds_dwordx4 v[6:7], off
	v_lshl_add_u64 v[2:3], v[2:3], 0, s[12:13]
	s_mov_b32 m0, s52
	s_add_u32 s4, s42, 0x40080
	global_load_lds_dwordx4 v[2:3], off
	v_lshl_add_u64 v[2:3], v[4:5], 0, s[12:13]
	s_mov_b32 m0, s53
	s_addc_u32 s5, s43, 0
	global_load_lds_dwordx4 v[2:3], off
	s_add_i32 m0, s39, 0x1c000
	v_lshl_add_u64 v[2:3], s[4:5], 0, v[156:157]
	global_load_lds_dwordx4 v[2:3], off
	v_lshl_add_u64 v[2:3], s[4:5], 0, v[160:161]
	s_add_i32 m0, s39, 0x1e000
	v_lshlrev_b32_e32 v5, 2, v190
	global_load_lds_dwordx4 v[2:3], off
	s_waitcnt vmcnt(8)
	s_barrier
	v_and_b32_e32 v2, 3, v188
	v_lshlrev_b32_e32 v3, 4, v2
	v_lshl_or_b32 v4, v190, 6, v3
	v_and_b32_e32 v5, 32, v5
	v_lshl_or_b32 v193, s0, 6, v190
	v_bitop3_b32 v4, v4, s15, v5 bitop3:0xde
	v_lshlrev_b32_e32 v5, 6, v189
	s_movk_i32 s0, 0x3c0
	v_and_or_b32 v3, v5, s0, v3
	v_and_b32_e32 v5, 32, v192
	v_bitop3_b32 v194, s1, v3, v5 bitop3:0xf6
	v_cmp_eq_u32_e64 s[0:1], 0, v2
	v_lshl_or_b32 v195, v2, 3, s16
	v_lshlrev_b32_e32 v2, 8, v189
	v_and_b32_e32 v2, 0x38000, v2
	v_lshlrev_b32_e32 v3, 11, v12
	v_or3_b32 v2, v10, v2, v3
	v_add_u32_e32 v162, v2, v11
	v_lshlrev_b32_e32 v2, 4, v13
	v_and_b32_e32 v2, 0x78000, v2
	s_waitcnt vmcnt(6)
	s_cmpk_lt_u32 s14, 0x100
	v_or3_b32 v2, v10, v2, v3
	s_cselect_b64 s[14:15], -1, 0
	v_add_u32_e32 v164, v2, v11
	s_add_i32 s56, 0, 0x10000
	s_add_i32 s57, 0, 0x14000
	v_mbcnt_lo_u32_b32 v2, -1, 0
	s_ashr_i32 s54, s3, 31
	s_ashr_i32 s55, s2, 31
	v_mov_b32_e32 v163, v157
	v_mov_b32_e32 v165, v157
	v_mov_b64_e32 v[166:167], 0x200
	v_mov_b64_e32 v[168:169], 0x1ff
	v_add_u32_e32 v196, s56, v194
	v_add_u32_e32 v197, s57, v194
	v_add_u32_e32 v198, 0, v4
	v_mbcnt_hi_u32_b32 v199, -1, v2
	s_barrier
	s_mov_b32 s98, 0
	s_branch .LBB0_1332

; #define PG8_STAGE(bufoff, gbase, voff) do { _Pragma("unroll") for (int _i = 0; _i < 2; ++_i) \
;         __builtin_amdgcn_global_load_lds((const unsigned*)((const char*)(gbase) + (voff)[_i]), (LAS unsigned*)(lds + (bufoff) + ldsw + _i * 8192), 16, 0, 0); } while (0)
; #define PG8_WAIT_V(n) asm volatile("s_waitcnt vmcnt(" #n ")" ::: "memory")
; #define PG8_BAR __builtin_amdgcn_s_barrier()
; template <class Epi, bool ALIGN_EPI>
; __device__ __forceinline__ void gemm_phase(LAS unsigned char* lds, const Gemm g, const StaticOrder& S, const Epi& E) {
;     ...
;     PG8_STAGE(PG8_SB(0, 0), cB, voffB); PG8_STAGE(PG8_SB(0, 1), cB + hstep, voffB); PG8_STAGE(PG8_SA(0, 0), cA, voffA); PG8_STAGE(PG8_SA(0, 1), cA + hstep, voffA);
;     if (wr == 1) PG8_BAR;
;     PG8_WAIT_V(2); PG8_BAR;
;     PG8_STAGE(PG8_SB(1, 0), cB + kstep, voffB); PG8_STAGE(PG8_SA(1, 0), cA + kstep, voffA); PG8_STAGE(PG8_SB(1, 1), cB + hstep + kstep, voffB);
;     PG8_WAIT_V(6); PG8_BAR;
.LBB0_1422:
	s_lshl_b32 s5, s11, 5
	s_mov_b64 s[36:37], 0x80
	s_and_b32 s11, s5, 0x60
	s_add_i32 m0, s50, 0x18000
	v_lshl_add_u64 v[8:9], v[8:9], 0, s[36:37]
	s_ashr_i32 s55, s3, 31
	s_lshl_b32 s14, s10, 13
	s_lshl_b32 s15, s11, 7
	global_load_lds_dwordx4 v[8:9], off
	v_lshl_add_u64 v[6:7], v[6:7], 0, s[36:37]
	s_add_i32 m0, s50, 0x1a000
	s_add_i32 s56, s50, 0x8000
	s_add_i32 s57, s50, 0xa000
	global_load_lds_dwordx4 v[6:7], off
	v_lshl_add_u64 v[2:3], v[2:3], 0, s[36:37]
	s_mov_b32 m0, s56
	s_add_u32 s12, s8, 0x40080
	global_load_lds_dwordx4 v[2:3], off
	v_lshl_add_u64 v[2:3], v[4:5], 0, s[36:37]
	s_mov_b32 m0, s57
	s_addc_u32 s13, s9, 0
	global_load_lds_dwordx4 v[2:3], off
	s_add_i32 m0, s50, 0x1c000
	v_lshl_add_u64 v[2:3], s[12:13], 0, v[132:133]
	global_load_lds_dwordx4 v[2:3], off
	v_lshl_add_u64 v[2:3], s[12:13], 0, v[136:137]
	s_add_i32 m0, s50, 0x1e000
	s_sext_i32_i16 s5, s0
	global_load_lds_dwordx4 v[2:3], off
	s_waitcnt vmcnt(8)
	s_barrier
	v_and_b32_e32 v2, 15, v162
	v_lshlrev_b32_e32 v3, 1, v13
	v_lshlrev_b32_e32 v4, 6, v162
	s_movk_i32 s0, 0x3c0
	v_and_or_b32 v4, v4, s0, v3
	v_and_b32_e32 v5, 32, v163
	v_lshl_or_b32 v165, s10, 6, v2
	v_lshl_or_b32 v2, v2, 6, v3
	v_lshlrev_b32_e32 v3, 8, v162
	v_bitop3_b32 v166, s15, v4, v5 bitop3:0xf6
	v_and_b32_e32 v3, 0x38000, v3
	v_lshlrev_b32_e32 v4, 11, v12
	v_or3_b32 v3, v10, v3, v4
	v_add_u32_e32 v138, v3, v11
	v_lshlrev_b32_e32 v3, 4, v14
	s_waitcnt vmcnt(6)
	s_cmpk_lt_u32 s1, 0x100
	v_and_b32_e32 v3, 0x78000, v3
	v_bitop3_b32 v2, v2, s14, v5 bitop3:0xde
	s_cselect_b64 s[38:39], -1, 0
	v_or3_b32 v3, v10, v3, v4
	s_add_i32 s58, 0, 0x10000
	s_add_i32 s59, 0, 0x14000
	v_or_b32_e32 v167, s11, v13
	v_mov_b32_e32 v139, v133
	v_add_u32_e32 v140, v3, v11
	v_mov_b32_e32 v141, v133
	v_mov_b64_e32 v[142:143], 0xb00
	v_mov_b64_e32 v[144:145], 0xaff
	v_add_u32_e32 v168, s58, v166
	v_add_u32_e32 v169, s59, v166
	v_add_u32_e32 v170, 0, v2
	v_mov_b32_e32 v171, 0x358637bd
	s_mov_b32 s60, 0x800000
	s_movk_i32 s61, 0x1600
	s_barrier
	s_mov_b32 s98, 0
	s_branch .LBB0_1425

; #define PG8_STAGE(bufoff, gbase, voff) do { _Pragma("unroll") for (int _i = 0; _i < 2; ++_i) \
;         __builtin_amdgcn_global_load_lds((const unsigned*)((const char*)(gbase) + (voff)[_i]), (LAS unsigned*)(lds + (bufoff) + ldsw + _i * 8192), 16, 0, 0); } while (0)
; #define PG8_WAIT_V(n) asm volatile("s_waitcnt vmcnt(" #n ")" ::: "memory")
; #define PG8_BAR __builtin_amdgcn_s_barrier()
; template <class Epi, bool ALIGN_EPI>
; __device__ __forceinline__ void gemm_phase(LAS unsigned char* lds, const Gemm g, const StaticOrder& S, const Epi& E) {
;     ...
;     PG8_STAGE(PG8_SB(0, 0), cB, voffB); PG8_STAGE(PG8_SB(0, 1), cB + hstep, voffB); PG8_STAGE(PG8_SA(0, 0), cA, voffA); PG8_STAGE(PG8_SA(0, 1), cA + hstep, voffA);
;     if (wr == 1) PG8_BAR;
;     PG8_WAIT_V(2); PG8_BAR;
;     PG8_STAGE(PG8_SB(1, 0), cB + kstep, voffB); PG8_STAGE(PG8_SA(1, 0), cA + kstep, voffA); PG8_STAGE(PG8_SB(1, 1), cB + hstep + kstep, voffB);
;     PG8_WAIT_V(6); PG8_BAR;
.LBB0_1499:
	s_lshl_b32 s5, s5, 5
	s_mov_b64 s[8:9], 0x80
	s_and_b32 s5, s5, 0x60
	s_add_i32 m0, s26, 0x18000
	v_lshl_add_u64 v[6:7], v[6:7], 0, s[8:9]
	s_lshl_b32 s12, s0, 13
	s_lshl_b32 s13, s5, 7
	global_load_lds_dwordx4 v[6:7], off
	v_lshl_add_u64 v[4:5], v[4:5], 0, s[8:9]
	s_add_i32 m0, s26, 0x1a000
	s_add_i32 s31, s26, 0x8000
	s_add_i32 s33, s26, 0xa000
	global_load_lds_dwordx4 v[4:5], off
	v_lshl_add_u64 v[0:1], v[0:1], 0, s[8:9]
	s_mov_b32 m0, s31
	s_add_u32 s10, s16, 0xb0080
	global_load_lds_dwordx4 v[0:1], off
	v_lshl_add_u64 v[0:1], v[2:3], 0, s[8:9]
	s_mov_b32 m0, s33
	s_addc_u32 s11, s17, 0
	global_load_lds_dwordx4 v[0:1], off
	s_add_i32 m0, s26, 0x1c000
	v_lshl_add_u64 v[0:1], s[10:11], 0, v[130:131]
	global_load_lds_dwordx4 v[0:1], off
	v_lshl_add_u64 v[0:1], s[10:11], 0, v[134:135]
	s_add_i32 m0, s26, 0x1e000
	v_lshlrev_b32_e32 v3, 6, v153
	global_load_lds_dwordx4 v[0:1], off
	s_waitcnt vmcnt(8)
	s_barrier
	v_and_b32_e32 v0, 15, v153
	v_lshl_or_b32 v155, s0, 6, v0
	v_lshlrev_b32_e32 v1, 1, v10
	s_movk_i32 s0, 0x3c0
	v_lshl_or_b32 v0, v0, 6, v1
	v_and_b32_e32 v2, 32, v154
	v_and_or_b32 v1, v3, s0, v1
	v_bitop3_b32 v156, s13, v1, v2 bitop3:0xf6
	s_waitcnt vmcnt(6)
	s_cmpk_lt_u32 s4, 0x100
	v_add_u16_e32 v1, v8, v9
	v_bitop3_b32 v0, v0, s12, v2 bitop3:0xde
	s_cselect_b64 s[10:11], -1, 0
	v_lshrrev_b16_e32 v1, 1, v1
	s_add_i32 s37, 0, 0x10000
	s_add_i32 s38, 0, 0x14000
	s_sext_i32_i8 s42, s1
	s_ashr_i32 s36, s3, 31
	v_or_b32_e32 v157, s5, v10
	v_add_lshl_u32 v136, v11, v1, 1
	v_mov_b32_e32 v137, v131
	v_add_lshl_u32 v138, v12, v1, 1
	v_mov_b32_e32 v139, v131
	v_mov_b64_e32 v[140:141], 0x200
	v_mov_b64_e32 v[142:143], 0x1ff
	v_add_u32_e32 v158, s37, v156
	v_add_u32_e32 v159, s38, v156
	v_add_u32_e32 v160, 0, v0
	s_barrier
	s_mov_b32 s98, 0
	s_branch .LBB0_1502
